# v103 with even-layer gate rewritten: 8 channels (16 B) per lane, head = 16-lane DPP row, dwordx4 loads/stores (3+1 per token instead of 12+4), rcp-based silu
# speedup vs baseline: 1.0032x; 1.0001x over previous
.LBB0_880:
	s_or_b64 exec, exec, s[40:41]
	s_waitcnt lgkmcnt(0)
	s_barrier
	ds_read_b32 v0, v230
	s_movk_i32 s25, 0x47f
	s_waitcnt lgkmcnt(0)
	v_cmp_lt_i32_e64 s[40:41], s25, v0
	v_readfirstlane_b32 s25, v0
	v_lshl_add_u32 v1, v0, 1, v216
	s_cmpk_lt_i32 s25, 0x480
	s_movk_i32 s25, 0x900
	s_cselect_b64 s[48:49], -1, 0
	v_cmp_gt_i32_e32 vcc, s25, v1
	s_and_b64 s[50:51], s[48:49], vcc
	s_and_saveexec_b64 s[48:49], s[50:51]
	s_cbranch_execz .LBB0_875
	s_waitcnt vmcnt(1)
	v_mov_b32_e32 v2, v217
	v_lshlrev_b32_e32 v0, 5, v0
	v_ashrrev_i32_e32 v3, 4, v2
	v_and_b32_e32 v7, -4, v3
	v_lshl_add_u32 v43, v1, 4, v7
	v_bfe_u32 v1, v2, 3, 3
	v_readlane_b32 s25, v255, 4
	v_add3_u32 v0, v228, v0, v7
	v_and_b32_e32 v6, 63, v2
	v_or_b32_e32 v2, s25, v1
	v_mad_i64_i32 v[0:1], s[50:51], v0, s33, 0
	v_mov_b32_e32 v3, v17
	v_readlane_b32 s50, v252, 19
	v_lshlrev_b32_e32 v16, 3, v6
	v_lshlrev_b32_e32 v4, 4, v6
	v_mov_b32_e32 v5, v17
	v_lshl_add_u64 v[28:29], v[2:3], 2, s[12:13]
	v_lshlrev_b32_e32 v2, 5, v6
	v_lshl_or_b32 v0, v6, 2, v0
	v_readlane_b32 s51, v252, 20
	v_lshl_add_u64 v[26:27], s[6:7], 0, v[4:5]
	v_lshl_add_u64 v[30:31], s[44:45], 0, v[2:3]
	v_lshl_add_u64 v[32:33], s[46:47], 0, v[16:17]
	v_lshl_add_u64 v[34:35], s[50:51], 0, v[0:1]
	s_mov_b32 s25, 0
	v_lshlrev_b32_e32 v16, 1, v16
	s_and_b64 vcc, exec, s[10:11]
	s_cbranch_vccnz .LBB0_883
	v_and_b32_e32 v110, 15, v6
	v_lshlrev_b32_e32 v110, 5, v110
	global_load_dwordx4 v[114:117], v110, s[46:47] offset:16
	global_load_dwordx4 v[110:113], v110, s[46:47]
	v_mul_u32_u24_e32 v102, 12, v6
	v_mov_b32_e32 v103, 0
	s_mov_b64 s[52:53], 0xa921000
	v_lshl_add_u64 v[102:103], v[34:35], 0, v[102:103]
	v_lshl_add_u64 v[102:103], v[102:103], 0, s[52:53]
	s_mov_b64 s[52:53], 0x1800
	v_lshl_add_u64 v[104:105], v[102:103], 0, s[52:53]
	v_lshl_add_u64 v[106:107], v[104:105], 0, s[52:53]
	v_lshl_add_u64 v[108:109], v[106:107], 0, s[52:53]
	global_load_dwordx4 v[54:57], v[102:103], off
	global_load_dwordx4 v[58:61], v[102:103], off offset:1024
	global_load_dwordx4 v[62:65], v[102:103], off offset:3072
	global_load_dwordx4 v[66:69], v[104:105], off
	global_load_dwordx4 v[70:73], v[104:105], off offset:1024
	global_load_dwordx4 v[74:77], v[104:105], off offset:3072
	global_load_dwordx4 v[78:81], v[106:107], off
	global_load_dwordx4 v[82:85], v[106:107], off offset:1024
	global_load_dwordx4 v[86:89], v[106:107], off offset:3072
	global_load_dwordx4 v[90:93], v[108:109], off
	global_load_dwordx4 v[94:97], v[108:109], off offset:1024
	global_load_dwordx4 v[98:101], v[108:109], off offset:3072
	s_waitcnt vmcnt(9)
	v_lshlrev_b32_e32 v118, 16, v54
	v_lshlrev_b32_e32 v119, 16, v58
	v_and_b32_e32 v54, 0xffff0000, v54
	v_and_b32_e32 v120, 0xffff0000, v58
	v_add_f32_e32 v58, v118, v119
	v_add_f32_e32 v54, v54, v120
	v_lshlrev_b32_e32 v118, 16, v55
	v_lshlrev_b32_e32 v119, 16, v59
	v_and_b32_e32 v55, 0xffff0000, v55
	v_and_b32_e32 v120, 0xffff0000, v59
	v_add_f32_e32 v59, v118, v119
	v_add_f32_e32 v55, v55, v120
	v_lshlrev_b32_e32 v118, 16, v56
	v_lshlrev_b32_e32 v119, 16, v60
	v_and_b32_e32 v56, 0xffff0000, v56
	v_and_b32_e32 v120, 0xffff0000, v60
	v_add_f32_e32 v60, v118, v119
	v_add_f32_e32 v56, v56, v120
	v_lshlrev_b32_e32 v118, 16, v57
	v_lshlrev_b32_e32 v119, 16, v61
	v_and_b32_e32 v57, 0xffff0000, v57
	v_and_b32_e32 v120, 0xffff0000, v61
	v_add_f32_e32 v61, v118, v119
	v_add_f32_e32 v57, v57, v120
	v_mul_f32_e32 v118, v58, v58
	v_fmac_f32_e32 v118, v54, v54
	v_fmac_f32_e32 v118, v59, v59
	v_fmac_f32_e32 v118, v55, v55
	v_fmac_f32_e32 v118, v60, v60
	v_fmac_f32_e32 v118, v56, v56
	v_fmac_f32_e32 v118, v61, v61
	v_fmac_f32_e32 v118, v57, v57
	s_nop 1
	v_add_f32_dpp v119, v118, v118 row_ror:8 row_mask:0xf bank_mask:0xf
	s_nop 1
	v_add_f32_dpp v118, v119, v119 row_ror:4 row_mask:0xf bank_mask:0xf
	s_nop 1
	v_add_f32_dpp v119, v118, v118 row_ror:2 row_mask:0xf bank_mask:0xf
	s_nop 1
	v_add_f32_dpp v118, v119, v119 row_ror:1 row_mask:0xf bank_mask:0xf
	s_nop 0
	v_fmamk_f32 v118, v118, 0x3c000000, v231
	v_cmp_gt_f32_e32 vcc, s3, v118
	v_mul_f32_e32 v119, 0x4b800000, v118
	s_nop 0
	v_cndmask_b32_e32 v118, v118, v119, vcc
	v_rsq_f32_e32 v118, v118
	s_nop 0
	v_mul_f32_e32 v119, 0x45800000, v118
	v_cndmask_b32_e32 v118, v118, v119, vcc
	v_lshlrev_b32_e32 v119, 16, v62
	v_and_b32_e32 v120, 0xffff0000, v62
	v_mul_f32_e32 v121, 0xbfb8aa3b, v119
	v_mul_f32_e32 v122, 0xbfb8aa3b, v120
	v_mul_f32_e32 v58, v58, v118
	v_mul_f32_e32 v54, v54, v118
	v_exp_f32_e32 v121, v121
	v_exp_f32_e32 v122, v122
	v_mul_f32_e32 v58, v110, v58
	v_mul_f32_e32 v54, v111, v54
	v_add_f32_e32 v121, 1.0, v121
	v_add_f32_e32 v122, 1.0, v122
	s_nop 0
	v_rcp_f32_e32 v121, v121
	v_rcp_f32_e32 v122, v122
	s_nop 0
	v_mul_f32_e32 v119, v119, v121
	v_mul_f32_e32 v120, v120, v122
	v_mul_f32_e32 v58, v119, v58
	v_mul_f32_e32 v54, v120, v54
	v_cvt_pk_bf16_f32 v62, v58, v54
	v_lshlrev_b32_e32 v119, 16, v63
	v_and_b32_e32 v120, 0xffff0000, v63
	v_mul_f32_e32 v121, 0xbfb8aa3b, v119
	v_mul_f32_e32 v122, 0xbfb8aa3b, v120
	v_mul_f32_e32 v59, v59, v118
	v_mul_f32_e32 v55, v55, v118
	v_exp_f32_e32 v121, v121
	v_exp_f32_e32 v122, v122
	v_mul_f32_e32 v59, v112, v59
	v_mul_f32_e32 v55, v113, v55
	v_add_f32_e32 v121, 1.0, v121
	v_add_f32_e32 v122, 1.0, v122
	s_nop 0
	v_rcp_f32_e32 v121, v121
	v_rcp_f32_e32 v122, v122
	s_nop 0
	v_mul_f32_e32 v119, v119, v121
	v_mul_f32_e32 v120, v120, v122
	v_mul_f32_e32 v59, v119, v59
	v_mul_f32_e32 v55, v120, v55
	v_cvt_pk_bf16_f32 v63, v59, v55
	v_lshlrev_b32_e32 v119, 16, v64
	v_and_b32_e32 v120, 0xffff0000, v64
	v_mul_f32_e32 v121, 0xbfb8aa3b, v119
	v_mul_f32_e32 v122, 0xbfb8aa3b, v120
	v_mul_f32_e32 v60, v60, v118
	v_mul_f32_e32 v56, v56, v118
	v_exp_f32_e32 v121, v121
	v_exp_f32_e32 v122, v122
	v_mul_f32_e32 v60, v114, v60
	v_mul_f32_e32 v56, v115, v56
	v_add_f32_e32 v121, 1.0, v121
	v_add_f32_e32 v122, 1.0, v122
	s_nop 0
	v_rcp_f32_e32 v121, v121
	v_rcp_f32_e32 v122, v122
	s_nop 0
	v_mul_f32_e32 v119, v119, v121
	v_mul_f32_e32 v120, v120, v122
	v_mul_f32_e32 v60, v119, v60
	v_mul_f32_e32 v56, v120, v56
	v_cvt_pk_bf16_f32 v64, v60, v56
	v_lshlrev_b32_e32 v119, 16, v65
	v_and_b32_e32 v120, 0xffff0000, v65
	v_mul_f32_e32 v121, 0xbfb8aa3b, v119
	v_mul_f32_e32 v122, 0xbfb8aa3b, v120
	v_mul_f32_e32 v61, v61, v118
	v_mul_f32_e32 v57, v57, v118
	v_exp_f32_e32 v121, v121
	v_exp_f32_e32 v122, v122
	v_mul_f32_e32 v61, v116, v61
	v_mul_f32_e32 v57, v117, v57
	v_add_f32_e32 v121, 1.0, v121
	v_add_f32_e32 v122, 1.0, v122
	s_nop 0
	v_rcp_f32_e32 v121, v121
	v_rcp_f32_e32 v122, v122
	s_nop 0
	v_mul_f32_e32 v119, v119, v121
	v_mul_f32_e32 v120, v120, v122
	v_mul_f32_e32 v61, v119, v61
	v_mul_f32_e32 v57, v120, v57
	v_cvt_pk_bf16_f32 v65, v61, v57
	global_store_dwordx4 v[102:103], v[62:65], off
	s_waitcnt vmcnt(7)
	v_lshlrev_b32_e32 v118, 16, v66
	v_lshlrev_b32_e32 v119, 16, v70
	v_and_b32_e32 v66, 0xffff0000, v66
	v_and_b32_e32 v120, 0xffff0000, v70
	v_add_f32_e32 v70, v118, v119
	v_add_f32_e32 v66, v66, v120
	v_lshlrev_b32_e32 v118, 16, v67
	v_lshlrev_b32_e32 v119, 16, v71
	v_and_b32_e32 v67, 0xffff0000, v67
	v_and_b32_e32 v120, 0xffff0000, v71
	v_add_f32_e32 v71, v118, v119
	v_add_f32_e32 v67, v67, v120
	v_lshlrev_b32_e32 v118, 16, v68
	v_lshlrev_b32_e32 v119, 16, v72
	v_and_b32_e32 v68, 0xffff0000, v68
	v_and_b32_e32 v120, 0xffff0000, v72
	v_add_f32_e32 v72, v118, v119
	v_add_f32_e32 v68, v68, v120
	v_lshlrev_b32_e32 v118, 16, v69
	v_lshlrev_b32_e32 v119, 16, v73
	v_and_b32_e32 v69, 0xffff0000, v69
	v_and_b32_e32 v120, 0xffff0000, v73
	v_add_f32_e32 v73, v118, v119
	v_add_f32_e32 v69, v69, v120
	v_mul_f32_e32 v118, v70, v70
	v_fmac_f32_e32 v118, v66, v66
	v_fmac_f32_e32 v118, v71, v71
	v_fmac_f32_e32 v118, v67, v67
	v_fmac_f32_e32 v118, v72, v72
	v_fmac_f32_e32 v118, v68, v68
	v_fmac_f32_e32 v118, v73, v73
	v_fmac_f32_e32 v118, v69, v69
	s_nop 1
	v_add_f32_dpp v119, v118, v118 row_ror:8 row_mask:0xf bank_mask:0xf
	s_nop 1
	v_add_f32_dpp v118, v119, v119 row_ror:4 row_mask:0xf bank_mask:0xf
	s_nop 1
	v_add_f32_dpp v119, v118, v118 row_ror:2 row_mask:0xf bank_mask:0xf
	s_nop 1
	v_add_f32_dpp v118, v119, v119 row_ror:1 row_mask:0xf bank_mask:0xf
	s_nop 0
	v_fmamk_f32 v118, v118, 0x3c000000, v231
	v_cmp_gt_f32_e32 vcc, s3, v118
	v_mul_f32_e32 v119, 0x4b800000, v118
	s_nop 0
	v_cndmask_b32_e32 v118, v118, v119, vcc
	v_rsq_f32_e32 v118, v118
	s_nop 0
	v_mul_f32_e32 v119, 0x45800000, v118
	v_cndmask_b32_e32 v118, v118, v119, vcc
	v_lshlrev_b32_e32 v119, 16, v74
	v_and_b32_e32 v120, 0xffff0000, v74
	v_mul_f32_e32 v121, 0xbfb8aa3b, v119
	v_mul_f32_e32 v122, 0xbfb8aa3b, v120
	v_mul_f32_e32 v70, v70, v118
	v_mul_f32_e32 v66, v66, v118
	v_exp_f32_e32 v121, v121
	v_exp_f32_e32 v122, v122
	v_mul_f32_e32 v70, v110, v70
	v_mul_f32_e32 v66, v111, v66
	v_add_f32_e32 v121, 1.0, v121
	v_add_f32_e32 v122, 1.0, v122
	s_nop 0
	v_rcp_f32_e32 v121, v121
	v_rcp_f32_e32 v122, v122
	s_nop 0
	v_mul_f32_e32 v119, v119, v121
	v_mul_f32_e32 v120, v120, v122
	v_mul_f32_e32 v70, v119, v70
	v_mul_f32_e32 v66, v120, v66
	v_cvt_pk_bf16_f32 v74, v70, v66
	v_lshlrev_b32_e32 v119, 16, v75
	v_and_b32_e32 v120, 0xffff0000, v75
	v_mul_f32_e32 v121, 0xbfb8aa3b, v119
	v_mul_f32_e32 v122, 0xbfb8aa3b, v120
	v_mul_f32_e32 v71, v71, v118
	v_mul_f32_e32 v67, v67, v118
	v_exp_f32_e32 v121, v121
	v_exp_f32_e32 v122, v122
	v_mul_f32_e32 v71, v112, v71
	v_mul_f32_e32 v67, v113, v67
	v_add_f32_e32 v121, 1.0, v121
	v_add_f32_e32 v122, 1.0, v122
	s_nop 0
	v_rcp_f32_e32 v121, v121
	v_rcp_f32_e32 v122, v122
	s_nop 0
	v_mul_f32_e32 v119, v119, v121
	v_mul_f32_e32 v120, v120, v122
	v_mul_f32_e32 v71, v119, v71
	v_mul_f32_e32 v67, v120, v67
	v_cvt_pk_bf16_f32 v75, v71, v67
	v_lshlrev_b32_e32 v119, 16, v76
	v_and_b32_e32 v120, 0xffff0000, v76
	v_mul_f32_e32 v121, 0xbfb8aa3b, v119
	v_mul_f32_e32 v122, 0xbfb8aa3b, v120
	v_mul_f32_e32 v72, v72, v118
	v_mul_f32_e32 v68, v68, v118
	v_exp_f32_e32 v121, v121
	v_exp_f32_e32 v122, v122
	v_mul_f32_e32 v72, v114, v72
	v_mul_f32_e32 v68, v115, v68
	v_add_f32_e32 v121, 1.0, v121
	v_add_f32_e32 v122, 1.0, v122
	s_nop 0
	v_rcp_f32_e32 v121, v121
	v_rcp_f32_e32 v122, v122
	s_nop 0
	v_mul_f32_e32 v119, v119, v121
	v_mul_f32_e32 v120, v120, v122
	v_mul_f32_e32 v72, v119, v72
	v_mul_f32_e32 v68, v120, v68
	v_cvt_pk_bf16_f32 v76, v72, v68
	v_lshlrev_b32_e32 v119, 16, v77
	v_and_b32_e32 v120, 0xffff0000, v77
	v_mul_f32_e32 v121, 0xbfb8aa3b, v119
	v_mul_f32_e32 v122, 0xbfb8aa3b, v120
	v_mul_f32_e32 v73, v73, v118
	v_mul_f32_e32 v69, v69, v118
	v_exp_f32_e32 v121, v121
	v_exp_f32_e32 v122, v122
	v_mul_f32_e32 v73, v116, v73
	v_mul_f32_e32 v69, v117, v69
	v_add_f32_e32 v121, 1.0, v121
	v_add_f32_e32 v122, 1.0, v122
	s_nop 0
	v_rcp_f32_e32 v121, v121
	v_rcp_f32_e32 v122, v122
	s_nop 0
	v_mul_f32_e32 v119, v119, v121
	v_mul_f32_e32 v120, v120, v122
	v_mul_f32_e32 v73, v119, v73
	v_mul_f32_e32 v69, v120, v69
	v_cvt_pk_bf16_f32 v77, v73, v69
	global_store_dwordx4 v[104:105], v[74:77], off
	s_waitcnt vmcnt(5)
	v_lshlrev_b32_e32 v118, 16, v78
	v_lshlrev_b32_e32 v119, 16, v82
	v_and_b32_e32 v78, 0xffff0000, v78
	v_and_b32_e32 v120, 0xffff0000, v82
	v_add_f32_e32 v82, v118, v119
	v_add_f32_e32 v78, v78, v120
	v_lshlrev_b32_e32 v118, 16, v79
	v_lshlrev_b32_e32 v119, 16, v83
	v_and_b32_e32 v79, 0xffff0000, v79
	v_and_b32_e32 v120, 0xffff0000, v83
	v_add_f32_e32 v83, v118, v119
	v_add_f32_e32 v79, v79, v120
	v_lshlrev_b32_e32 v118, 16, v80
	v_lshlrev_b32_e32 v119, 16, v84
	v_and_b32_e32 v80, 0xffff0000, v80
	v_and_b32_e32 v120, 0xffff0000, v84
	v_add_f32_e32 v84, v118, v119
	v_add_f32_e32 v80, v80, v120
	v_lshlrev_b32_e32 v118, 16, v81
	v_lshlrev_b32_e32 v119, 16, v85
	v_and_b32_e32 v81, 0xffff0000, v81
	v_and_b32_e32 v120, 0xffff0000, v85
	v_add_f32_e32 v85, v118, v119
	v_add_f32_e32 v81, v81, v120
	v_mul_f32_e32 v118, v82, v82
	v_fmac_f32_e32 v118, v78, v78
	v_fmac_f32_e32 v118, v83, v83
	v_fmac_f32_e32 v118, v79, v79
	v_fmac_f32_e32 v118, v84, v84
	v_fmac_f32_e32 v118, v80, v80
	v_fmac_f32_e32 v118, v85, v85
	v_fmac_f32_e32 v118, v81, v81
	s_nop 1
	v_add_f32_dpp v119, v118, v118 row_ror:8 row_mask:0xf bank_mask:0xf
	s_nop 1
	v_add_f32_dpp v118, v119, v119 row_ror:4 row_mask:0xf bank_mask:0xf
	s_nop 1
	v_add_f32_dpp v119, v118, v118 row_ror:2 row_mask:0xf bank_mask:0xf
	s_nop 1
	v_add_f32_dpp v118, v119, v119 row_ror:1 row_mask:0xf bank_mask:0xf
	s_nop 0
	v_fmamk_f32 v118, v118, 0x3c000000, v231
	v_cmp_gt_f32_e32 vcc, s3, v118
	v_mul_f32_e32 v119, 0x4b800000, v118
	s_nop 0
	v_cndmask_b32_e32 v118, v118, v119, vcc
	v_rsq_f32_e32 v118, v118
	s_nop 0
	v_mul_f32_e32 v119, 0x45800000, v118
	v_cndmask_b32_e32 v118, v118, v119, vcc
	v_lshlrev_b32_e32 v119, 16, v86
	v_and_b32_e32 v120, 0xffff0000, v86
	v_mul_f32_e32 v121, 0xbfb8aa3b, v119
	v_mul_f32_e32 v122, 0xbfb8aa3b, v120
	v_mul_f32_e32 v82, v82, v118
	v_mul_f32_e32 v78, v78, v118
	v_exp_f32_e32 v121, v121
	v_exp_f32_e32 v122, v122
	v_mul_f32_e32 v82, v110, v82
	v_mul_f32_e32 v78, v111, v78
	v_add_f32_e32 v121, 1.0, v121
	v_add_f32_e32 v122, 1.0, v122
	s_nop 0
	v_rcp_f32_e32 v121, v121
	v_rcp_f32_e32 v122, v122
	s_nop 0
	v_mul_f32_e32 v119, v119, v121
	v_mul_f32_e32 v120, v120, v122
	v_mul_f32_e32 v82, v119, v82
	v_mul_f32_e32 v78, v120, v78
	v_cvt_pk_bf16_f32 v86, v82, v78
	v_lshlrev_b32_e32 v119, 16, v87
	v_and_b32_e32 v120, 0xffff0000, v87
	v_mul_f32_e32 v121, 0xbfb8aa3b, v119
	v_mul_f32_e32 v122, 0xbfb8aa3b, v120
	v_mul_f32_e32 v83, v83, v118
	v_mul_f32_e32 v79, v79, v118
	v_exp_f32_e32 v121, v121
	v_exp_f32_e32 v122, v122
	v_mul_f32_e32 v83, v112, v83
	v_mul_f32_e32 v79, v113, v79
	v_add_f32_e32 v121, 1.0, v121
	v_add_f32_e32 v122, 1.0, v122
	s_nop 0
	v_rcp_f32_e32 v121, v121
	v_rcp_f32_e32 v122, v122
	s_nop 0
	v_mul_f32_e32 v119, v119, v121
	v_mul_f32_e32 v120, v120, v122
	v_mul_f32_e32 v83, v119, v83
	v_mul_f32_e32 v79, v120, v79
	v_cvt_pk_bf16_f32 v87, v83, v79
	v_lshlrev_b32_e32 v119, 16, v88
	v_and_b32_e32 v120, 0xffff0000, v88
	v_mul_f32_e32 v121, 0xbfb8aa3b, v119
	v_mul_f32_e32 v122, 0xbfb8aa3b, v120
	v_mul_f32_e32 v84, v84, v118
	v_mul_f32_e32 v80, v80, v118
	v_exp_f32_e32 v121, v121
	v_exp_f32_e32 v122, v122
	v_mul_f32_e32 v84, v114, v84
	v_mul_f32_e32 v80, v115, v80
	v_add_f32_e32 v121, 1.0, v121
	v_add_f32_e32 v122, 1.0, v122
	s_nop 0
	v_rcp_f32_e32 v121, v121
	v_rcp_f32_e32 v122, v122
	s_nop 0
	v_mul_f32_e32 v119, v119, v121
	v_mul_f32_e32 v120, v120, v122
	v_mul_f32_e32 v84, v119, v84
	v_mul_f32_e32 v80, v120, v80
	v_cvt_pk_bf16_f32 v88, v84, v80
	v_lshlrev_b32_e32 v119, 16, v89
	v_and_b32_e32 v120, 0xffff0000, v89
	v_mul_f32_e32 v121, 0xbfb8aa3b, v119
	v_mul_f32_e32 v122, 0xbfb8aa3b, v120
	v_mul_f32_e32 v85, v85, v118
	v_mul_f32_e32 v81, v81, v118
	v_exp_f32_e32 v121, v121
	v_exp_f32_e32 v122, v122
	v_mul_f32_e32 v85, v116, v85
	v_mul_f32_e32 v81, v117, v81
	v_add_f32_e32 v121, 1.0, v121
	v_add_f32_e32 v122, 1.0, v122
	s_nop 0
	v_rcp_f32_e32 v121, v121
	v_rcp_f32_e32 v122, v122
	s_nop 0
	v_mul_f32_e32 v119, v119, v121
	v_mul_f32_e32 v120, v120, v122
	v_mul_f32_e32 v85, v119, v85
	v_mul_f32_e32 v81, v120, v81
	v_cvt_pk_bf16_f32 v89, v85, v81
	global_store_dwordx4 v[106:107], v[86:89], off
	s_waitcnt vmcnt(3)
	v_lshlrev_b32_e32 v118, 16, v90
	v_lshlrev_b32_e32 v119, 16, v94
	v_and_b32_e32 v90, 0xffff0000, v90
	v_and_b32_e32 v120, 0xffff0000, v94
	v_add_f32_e32 v94, v118, v119
	v_add_f32_e32 v90, v90, v120
	v_lshlrev_b32_e32 v118, 16, v91
	v_lshlrev_b32_e32 v119, 16, v95
	v_and_b32_e32 v91, 0xffff0000, v91
	v_and_b32_e32 v120, 0xffff0000, v95
	v_add_f32_e32 v95, v118, v119
	v_add_f32_e32 v91, v91, v120
	v_lshlrev_b32_e32 v118, 16, v92
	v_lshlrev_b32_e32 v119, 16, v96
	v_and_b32_e32 v92, 0xffff0000, v92
	v_and_b32_e32 v120, 0xffff0000, v96
	v_add_f32_e32 v96, v118, v119
	v_add_f32_e32 v92, v92, v120
	v_lshlrev_b32_e32 v118, 16, v93
	v_lshlrev_b32_e32 v119, 16, v97
	v_and_b32_e32 v93, 0xffff0000, v93
	v_and_b32_e32 v120, 0xffff0000, v97
	v_add_f32_e32 v97, v118, v119
	v_add_f32_e32 v93, v93, v120
	v_mul_f32_e32 v118, v94, v94
	v_fmac_f32_e32 v118, v90, v90
	v_fmac_f32_e32 v118, v95, v95
	v_fmac_f32_e32 v118, v91, v91
	v_fmac_f32_e32 v118, v96, v96
	v_fmac_f32_e32 v118, v92, v92
	v_fmac_f32_e32 v118, v97, v97
	v_fmac_f32_e32 v118, v93, v93
	s_nop 1
	v_add_f32_dpp v119, v118, v118 row_ror:8 row_mask:0xf bank_mask:0xf
	s_nop 1
	v_add_f32_dpp v118, v119, v119 row_ror:4 row_mask:0xf bank_mask:0xf
	s_nop 1
	v_add_f32_dpp v119, v118, v118 row_ror:2 row_mask:0xf bank_mask:0xf
	s_nop 1
	v_add_f32_dpp v118, v119, v119 row_ror:1 row_mask:0xf bank_mask:0xf
	s_nop 0
	v_fmamk_f32 v118, v118, 0x3c000000, v231
	v_cmp_gt_f32_e32 vcc, s3, v118
	v_mul_f32_e32 v119, 0x4b800000, v118
	s_nop 0
	v_cndmask_b32_e32 v118, v118, v119, vcc
	v_rsq_f32_e32 v118, v118
	s_nop 0
	v_mul_f32_e32 v119, 0x45800000, v118
	v_cndmask_b32_e32 v118, v118, v119, vcc
	v_lshlrev_b32_e32 v119, 16, v98
	v_and_b32_e32 v120, 0xffff0000, v98
	v_mul_f32_e32 v121, 0xbfb8aa3b, v119
	v_mul_f32_e32 v122, 0xbfb8aa3b, v120
	v_mul_f32_e32 v94, v94, v118
	v_mul_f32_e32 v90, v90, v118
	v_exp_f32_e32 v121, v121
	v_exp_f32_e32 v122, v122
	v_mul_f32_e32 v94, v110, v94
	v_mul_f32_e32 v90, v111, v90
	v_add_f32_e32 v121, 1.0, v121
	v_add_f32_e32 v122, 1.0, v122
	s_nop 0
	v_rcp_f32_e32 v121, v121
	v_rcp_f32_e32 v122, v122
	s_nop 0
	v_mul_f32_e32 v119, v119, v121
	v_mul_f32_e32 v120, v120, v122
	v_mul_f32_e32 v94, v119, v94
	v_mul_f32_e32 v90, v120, v90
	v_cvt_pk_bf16_f32 v98, v94, v90
	v_lshlrev_b32_e32 v119, 16, v99
	v_and_b32_e32 v120, 0xffff0000, v99
	v_mul_f32_e32 v121, 0xbfb8aa3b, v119
	v_mul_f32_e32 v122, 0xbfb8aa3b, v120
	v_mul_f32_e32 v95, v95, v118
	v_mul_f32_e32 v91, v91, v118
	v_exp_f32_e32 v121, v121
	v_exp_f32_e32 v122, v122
	v_mul_f32_e32 v95, v112, v95
	v_mul_f32_e32 v91, v113, v91
	v_add_f32_e32 v121, 1.0, v121
	v_add_f32_e32 v122, 1.0, v122
	s_nop 0
	v_rcp_f32_e32 v121, v121
	v_rcp_f32_e32 v122, v122
	s_nop 0
	v_mul_f32_e32 v119, v119, v121
	v_mul_f32_e32 v120, v120, v122
	v_mul_f32_e32 v95, v119, v95
	v_mul_f32_e32 v91, v120, v91
	v_cvt_pk_bf16_f32 v99, v95, v91
	v_lshlrev_b32_e32 v119, 16, v100
	v_and_b32_e32 v120, 0xffff0000, v100
	v_mul_f32_e32 v121, 0xbfb8aa3b, v119
	v_mul_f32_e32 v122, 0xbfb8aa3b, v120
	v_mul_f32_e32 v96, v96, v118
	v_mul_f32_e32 v92, v92, v118
	v_exp_f32_e32 v121, v121
	v_exp_f32_e32 v122, v122
	v_mul_f32_e32 v96, v114, v96
	v_mul_f32_e32 v92, v115, v92
	v_add_f32_e32 v121, 1.0, v121
	v_add_f32_e32 v122, 1.0, v122
	s_nop 0
	v_rcp_f32_e32 v121, v121
	v_rcp_f32_e32 v122, v122
	s_nop 0
	v_mul_f32_e32 v119, v119, v121
	v_mul_f32_e32 v120, v120, v122
	v_mul_f32_e32 v96, v119, v96
	v_mul_f32_e32 v92, v120, v92
	v_cvt_pk_bf16_f32 v100, v96, v92
	v_lshlrev_b32_e32 v119, 16, v101
	v_and_b32_e32 v120, 0xffff0000, v101
	v_mul_f32_e32 v121, 0xbfb8aa3b, v119
	v_mul_f32_e32 v122, 0xbfb8aa3b, v120
	v_mul_f32_e32 v97, v97, v118
	v_mul_f32_e32 v93, v93, v118
	v_exp_f32_e32 v121, v121
	v_exp_f32_e32 v122, v122
	v_mul_f32_e32 v97, v116, v97
	v_mul_f32_e32 v93, v117, v93
	v_add_f32_e32 v121, 1.0, v121
	v_add_f32_e32 v122, 1.0, v122
	s_nop 0
	v_rcp_f32_e32 v121, v121
	v_rcp_f32_e32 v122, v122
	s_nop 0
	v_mul_f32_e32 v119, v119, v121
	v_mul_f32_e32 v120, v120, v122
	v_mul_f32_e32 v97, v119, v97
	v_mul_f32_e32 v93, v120, v93
	v_cvt_pk_bf16_f32 v101, v97, v93
	global_store_dwordx4 v[108:109], v[98:101], off
	s_branch .LBB0_875
	s_branch .LBB0_883
